# prologue low-rank weight conversion: eight element loads in flight instead of serialised masked loads
# speedup vs baseline: 1.0879x; 1.0026x over previous
.LBB0_93:
	s_andn2_b64 vcc, exec, s[6:7]
	s_cbranch_vccnz .LBB0_198
	s_load_dwordx2 s[28:29], s[24:25], 0x98
	s_waitcnt lgkmcnt(0)
	s_load_dwordx4 s[12:15], s[24:25], 0xa8
	v_and_b32_e32 v7, 0x78, v58
	v_lshlrev_b32_e32 v2, 1, v7
	v_mov_b32_e32 v3, 0
	v_lshl_add_u64 v[4:5], s[26:27], 0, v[2:3]
	s_mov_b64 s[4:5], 0x1d80000
	v_lshlrev_b32_e32 v6, 9, v7
	v_lshl_add_u64 v[4:5], v[4:5], 0, s[4:5]
	v_cmp_lt_u32_e64 s[4:5], 63, v7
	v_cmp_gt_u32_e64 s[6:7], 64, v7
	v_or_b32_e32 v8, 0x200, v6
	v_or_b32_e32 v10, 0x400, v6
	v_or_b32_e32 v12, 0x600, v6
	v_or_b32_e32 v14, 0x800, v6
	v_or_b32_e32 v16, 0xa00, v6
	v_or_b32_e32 v18, 0xc00, v6
	v_or_b32_e32 v20, 0xe00, v6
	v_mov_b32_e32 v7, v3
	v_mov_b32_e32 v9, v3
	v_mov_b32_e32 v11, v3
	v_mov_b32_e32 v13, v3
	v_mov_b32_e32 v15, v3
	v_mov_b32_e32 v17, v3
	v_mov_b32_e32 v19, v3
	v_mov_b32_e32 v21, v3
	s_movk_i32 s38, 0x1ff
	s_movk_i32 s39, 0x3ff
	s_mov_b32 s40, s16
	s_mul_hi_i32 s8, s16, 0x66666667
	s_lshr_b32 s9, s8, 31
	s_ashr_i32 s8, s8, 1
	s_add_i32 s8, s8, s9
	s_mul_i32 s9, s8, 5
	s_add_i32 s9, s9, 1
	s_cmp_lg_u32 s9, s16
	s_cbranch_scc1 .Llr_skip
	s_cmpk_gt_i32 s16, 0x77f
	s_cbranch_scc1 .Llr_skip
	v_lshl_or_b32 v2, s8, 6, v1
	v_ashrrev_i32_e32 v22, 4, v2
	v_and_b32_e32 v23, 0x78, v58
	v_cmp_ge_u32_e64 s[4:5], s38, v22
	v_cmp_ge_u32_e64 s[6:7], s39, v22
	s_andn2_b64 s[30:31], s[6:7], s[4:5]
	v_cmp_gt_u32_e64 s[8:9], 64, v23
	s_and_b64 s[34:35], s[4:5], s[8:9]
	s_andn2_b64 s[36:37], s[30:31], s[8:9]
	s_or_b64 s[34:35], s[34:35], s[36:37]
	s_orn2_b64 s[8:9], s[34:35], s[6:7]
	v_add_u32_e32 v24, 0xfffffc00, v22
	v_add_u32_e32 v25, 0xfffffe00, v22
	v_cndmask_b32_e64 v24, v24, v25, s[6:7]
	v_cndmask_b32_e64 v24, v24, v22, s[4:5]
	v_and_b32_e32 v25, 63, v23
	v_cndmask_b32_e64 v25, v23, v25, s[6:7]
	v_lshlrev_b32_e32 v24, 2, v24
	v_lshl_add_u32 v24, v25, 11, v24
	s_waitcnt lgkmcnt(0)
	v_mov_b32_e32 v26, s14
	v_mov_b32_e32 v27, s15
	v_mov_b32_e32 v28, s12
	v_mov_b32_e32 v29, s13
	v_cndmask_b32_e64 v26, v26, v28, s[6:7]
	v_cndmask_b32_e64 v27, v27, v29, s[6:7]
	v_mov_b32_e32 v28, s28
	v_mov_b32_e32 v29, s29
	v_cndmask_b32_e64 v26, v26, v28, s[4:5]
	v_cndmask_b32_e64 v27, v27, v29, s[4:5]
	v_add_co_u32_e32 v26, vcc, v26, v24
	s_nop 1
	v_addc_co_u32_e32 v27, vcc, 0, v27, vcc
	v_add_co_u32_e32 v28, vcc, 0x1000, v26
	s_nop 1
	v_addc_co_u32_e32 v29, vcc, 0, v27, vcc
	v_add_co_u32_e32 v30, vcc, 0x2000, v26
	s_nop 1
	v_addc_co_u32_e32 v31, vcc, 0, v27, vcc
	v_add_co_u32_e32 v32, vcc, 0x3000, v26
	s_nop 1
	v_addc_co_u32_e32 v33, vcc, 0, v27, vcc
	global_load_dword v10, v[26:27], off
	global_load_dword v11, v[26:27], off offset:2048
	global_load_dword v12, v[28:29], off
	global_load_dword v13, v[28:29], off offset:2048
	global_load_dword v14, v[30:31], off
	global_load_dword v15, v[30:31], off offset:2048
	global_load_dword v16, v[32:33], off
	global_load_dword v17, v[32:33], off offset:2048
	s_add_u32 s10, s26, 0x1d80000
	s_addc_u32 s11, s27, 0
	v_lshlrev_b32_e32 v24, 8, v22
	v_lshl_add_u32 v24, v23, 1, v24
	s_waitcnt vmcnt(0)
	v_cndmask_b32_e64 v10, 0, v10, s[8:9]
	v_cndmask_b32_e64 v11, 0, v11, s[8:9]
	v_cndmask_b32_e64 v12, 0, v12, s[8:9]
	v_cndmask_b32_e64 v13, 0, v13, s[8:9]
	v_cndmask_b32_e64 v14, 0, v14, s[8:9]
	v_cndmask_b32_e64 v15, 0, v15, s[8:9]
	v_cndmask_b32_e64 v16, 0, v16, s[8:9]
	v_cndmask_b32_e64 v17, 0, v17, s[8:9]
	v_cvt_pk_bf16_f32 v18, v10, v11
	v_cvt_pk_bf16_f32 v19, v12, v13
	v_cvt_pk_bf16_f32 v20, v14, v15
	v_cvt_pk_bf16_f32 v21, v16, v17
	global_store_dwordx4 v24, v[18:21], s[10:11]
.Llr_skip:
.LBB0_194:
	s_add_u32 s4, s26, 0x1e40000
	v_and_b32_e32 v2, 56, v58
	s_addc_u32 s5, s27, 0
	s_lshl_b32 s6, s3, 8
	s_lshl_b32 s7, s17, 5
	s_lshl_b32 s3, s3, 5
	s_lshl_b32 s8, s17, 2
	v_mov_b32_e32 v3, 0
	v_lshlrev_b32_e32 v6, 6, v2
	s_add_i32 s6, s6, s7
	s_lshl_b32 s7, s19, 8
	s_add_i32 s3, s3, s8
	s_lshl_b32 s8, s19, 5
	v_lshlrev_b32_e32 v4, 1, v2
	s_mov_b32 s9, s16
	s_branch .LBB0_196
